# v27 plus diff-loop ALiBi branch converted from exec-mask divergence to scalar wave-uniform branches
# baseline (speedup 1.0000x reference)
; template <int DQK, bool ALIBI>
; DI void attn_pass(const u16* __restrict__ Qp, int ldq, const u16* __restrict__ Kp, int ldk, const u16* __restrict__ VTp,
;                   int seq_start, int kt_lo, int kt_hi, int q0, float slope2, f32x16 (&O)[4], float& lsum, char* lds) {
;     ...
;     if (ALIBI) {
;       const float dq = qpos - (float)kb;
;       if (kb + 64 <= qw0 || kb > qw0 + 31) {
;         const float sl = (kb + 64 <= qw0) ? slope2 : -slope2;
;         const float T0 = -sl * dq, T1 = T0 + 32.f * sl;
; #pragma unroll
;         for (int i = 0; i < 16; ++i) {
;           S0[i] = fmaf(sl, (float)((i & 3) + 8 * (i >> 2)), T0);
;           S1[i] = fmaf(sl, (float)((i & 3) + 8 * (i >> 2)), T1);
;         }
;       } else {
; #pragma unroll
;         for (int i = 0; i < 16; ++i) {
;           S0[i] = -slope2 * fabsf(dq - (float)((i & 3) + 8 * (i >> 2)));
;           S1[i] = -slope2 * fabsf(dq - 32.f - (float)((i & 3) + 8 * (i >> 2)));
;         }
;       }
.LBB0_1149:
	v_readfirstlane_b32 s46, v129
	v_cvt_f32_u32_e32 v66, s89
	s_add_i32 s88, s89, 64
	v_cmp_le_i32_e32 vcc, s88, v129
	v_sub_f32_e32 v144, v154, v66
	s_cmp_gt_i32 s88, s46
	s_cbranch_scc0 .Lmy_dif_lin
	s_or_b32 s47, s46, 31
	s_cmp_le_i32 s89, s47
	s_cbranch_scc0 .Lmy_dif_lin
	v_add_f32_e32 v68, s38, v144
	v_add_f32_e32 v69, s39, v144
	v_add_f32_e32 v84, s74, v144
	v_add_f32_e32 v85, s75, v144
	v_add_f32_e32 v67, -1.0, v144
	v_add_f32_e32 v66, 0xc2000000, v144
	v_add_f32_e32 v72, s18, v144
	v_add_f32_e32 v73, s19, v144
	v_add_f32_e32 v76, s4, v144
	v_add_f32_e32 v77, s5, v144
	v_add_f32_e32 v82, s24, v144
	v_add_f32_e32 v83, s25, v144
	v_add_f32_e32 v86, s22, v144
	v_add_f32_e32 v87, s23, v144
	v_and_b32_e32 v69, 0x7fffffff, v69
	v_and_b32_e32 v68, 0x7fffffff, v68
	v_and_b32_e32 v85, 0x7fffffff, v85
	v_and_b32_e32 v84, 0x7fffffff, v84
	v_mov_b32_e32 v131, v130
	v_add_f32_e32 v166, -1.0, v66
	v_add_f32_e32 v70, s38, v66
	v_add_f32_e32 v71, s39, v66
	v_add_f32_e32 v74, s18, v66
	v_add_f32_e32 v75, s19, v66
	v_add_f32_e32 v78, s4, v66
	v_add_f32_e32 v79, s5, v66
	v_add_f32_e32 v80, s34, v144
	v_add_f32_e32 v81, s35, v144
	v_add_f32_e32 v160, s34, v66
	v_add_f32_e32 v161, s35, v66
	v_add_f32_e32 v162, s24, v66
	v_add_f32_e32 v163, s25, v66
	v_add_f32_e32 v164, s74, v66
	v_add_f32_e32 v165, s75, v66
	v_and_b32_e32 v73, 0x7fffffff, v73
	v_and_b32_e32 v72, 0x7fffffff, v72
	v_and_b32_e32 v77, 0x7fffffff, v77
	v_and_b32_e32 v76, 0x7fffffff, v76
	v_and_b32_e32 v83, 0x7fffffff, v83
	v_and_b32_e32 v82, 0x7fffffff, v82
	v_and_b32_e32 v87, 0x7fffffff, v87
	v_and_b32_e32 v86, 0x7fffffff, v86
	v_and_b32_e32 v144, 0x7fffffff, v144
	v_and_b32_e32 v145, 0x7fffffff, v67
	v_mul_f32_e32 v94, v84, v130
	v_mul_f32_e32 v95, v85, v131
	v_mul_f32_e32 v84, v68, v130
	v_mul_f32_e32 v85, v69, v131
	v_add_f32_e32 v68, s22, v66
	v_add_f32_e32 v69, s23, v66
	v_and_b32_e32 v81, 0x7fffffff, v81
	v_and_b32_e32 v80, 0x7fffffff, v80
	v_mul_f32_e32 v96, v86, v130
	v_mul_f32_e32 v97, v87, v131
	v_mul_f32_e32 v92, v82, v130
	v_mul_f32_e32 v93, v83, v131
	v_mul_f32_e32 v88, v76, v130
	v_mul_f32_e32 v89, v77, v131
	v_mul_f32_e32 v86, v72, v130
	v_mul_f32_e32 v87, v73, v131
	v_mul_f32_e32 v82, v144, v134
	v_mul_f32_e32 v83, v145, v135
	v_and_b32_e32 v145, 0x7fffffff, v71
	v_and_b32_e32 v144, 0x7fffffff, v70
	v_and_b32_e32 v71, 0x7fffffff, v75
	v_and_b32_e32 v70, 0x7fffffff, v74
	v_and_b32_e32 v73, 0x7fffffff, v79
	v_and_b32_e32 v72, 0x7fffffff, v78
	v_and_b32_e32 v75, 0x7fffffff, v161
	v_and_b32_e32 v74, 0x7fffffff, v160
	v_and_b32_e32 v77, 0x7fffffff, v163
	v_and_b32_e32 v76, 0x7fffffff, v162
	v_and_b32_e32 v79, 0x7fffffff, v165
	v_and_b32_e32 v78, 0x7fffffff, v164
	v_and_b32_e32 v69, 0x7fffffff, v69
	v_and_b32_e32 v68, 0x7fffffff, v68
	v_and_b32_e32 v66, 0x7fffffff, v66
	v_and_b32_e32 v67, 0x7fffffff, v166
	v_mul_f32_e32 v90, v80, v130
	v_mul_f32_e32 v91, v81, v131
	v_mul_f32_e32 v80, v68, v130
	v_mul_f32_e32 v81, v69, v131
	v_mul_f32_e32 v78, v78, v130
	v_mul_f32_e32 v79, v79, v131
	v_mul_f32_e32 v76, v76, v130
	v_mul_f32_e32 v77, v77, v131
	v_mul_f32_e32 v74, v74, v130
	v_mul_f32_e32 v75, v75, v131
	v_mul_f32_e32 v72, v72, v130
	v_mul_f32_e32 v73, v73, v131
	v_mul_f32_e32 v70, v70, v130
	v_mul_f32_e32 v71, v71, v131
	v_mul_f32_e32 v68, v144, v130
	v_mul_f32_e32 v69, v145, v131
	v_mul_f32_e32 v66, v66, v134
	v_mul_f32_e32 v67, v67, v135
	s_branch .LBB0_1153
.Lmy_dif_lin:
	v_cndmask_b32_e64 v145, -v149, v149, vcc
	v_xor_b32_e32 v192, 0x80000000, v145
	v_mul_f32_e32 v80, v144, v192
	v_mul_f32_e32 v81, v145, v193
	v_fma_f32 v160, v144, v192, v81
	v_fma_f32 v161, v145, v193, v80
	v_mov_b32_e32 v144, v145
	v_fma_f32 v82, 0, v145, v80
	v_fma_f32 v66, 0, v145, v160
	v_add_f32_e32 v83, v145, v80
	v_add_f32_e32 v67, v145, v160
	v_fma_f32 v84, v144, s20, v80
	v_fma_f32 v85, v144, s21, v80
	v_fma_f32 v68, v144, s20, v160
	v_fma_f32 v69, v144, s21, v160
	v_fma_f32 v86, v144, s8, v80
	v_fma_f32 v87, v144, s9, v80
	v_fma_f32 v70, v144, s8, v160
	v_fma_f32 v71, v144, s9, v160
	v_fma_f32 v88, v144, s26, v80
	v_fma_f32 v89, v144, s27, v80
	v_fma_f32 v72, v144, s26, v160
	v_fma_f32 v73, v144, s27, v160
	v_fma_f32 v90, v144, s28, v80
	v_fma_f32 v91, v144, s29, v80
	v_fma_f32 v74, v144, s28, v160
	v_fma_f32 v75, v144, s29, v160
	v_fma_f32 v92, v144, s30, v80
	v_fma_f32 v93, v144, s31, v80
	v_fma_f32 v76, v144, s30, v160
	v_fma_f32 v77, v144, s31, v160
	v_fma_f32 v94, v144, s36, v80
	v_fma_f32 v95, v144, s37, v80
	v_fma_f32 v78, v144, s36, v160
	v_fma_f32 v79, v144, s37, v160
	v_fma_f32 v96, v144, s78, v80
	v_fma_f32 v97, v144, s79, v80
	v_fma_f32 v80, v144, s78, v160
	v_fma_f32 v81, v144, s79, v160
; #define MFMA(a, b, c) __builtin_amdgcn_mfma_f32_32x32x16_bf16((a), (b), (c), 0, 0, 0)
; template <int DQK, bool ALIBI>
; DI void attn_pass(const u16* __restrict__ Qp, int ldq, const u16* __restrict__ Kp, int ldk, const u16* __restrict__ VTp,
;                   int seq_start, int kt_lo, int kt_hi, int q0, float slope2, f32x16 (&O)[4], float& lsum, char* lds) {
;     ...
;     bf16x8 k0[NKS], k1[NKS], vf[2][4];
; #pragma unroll
;     for (int ks = 0; ks < NKS; ++ks) {
;       k0[ks] = *(const bf16x8*)(Ks + r * KST + ks * 16 + h * 8);
;       k1[ks] = *(const bf16x8*)(Ks + (32 + r) * KST + ks * 16 + h * 8);
;     }
;     __builtin_amdgcn_sched_barrier(0);
; #pragma unroll
;     for (int ks = 0; ks < NKS; ++ks) {
;       S0 = MFMA(k0[ks], qf[ks], S0);
;       S1 = MFMA(k1[ks], qf[ks], S1);
;     }
;     if (kt + 1 < kt_hi) ATT_LSTORE(cur ^ 1);
;     if (kt + 2 < kt_hi) ATT_GLOAD(kt + 2);
; #pragma unroll
;     for (int s = 0; s < 2; ++s)
; #pragma unroll
;       for (int db = 0; db < 4; ++db) vf[s][db] = *(const bf16x8*)(Vs + (db * 32 + r) * 72 + s * 16 + h * 8);
;     __builtin_amdgcn_sched_barrier(0);
;     bf16x8 pf[2];
;     ...
;     ATT_SOFTMAX(S0);
;     __builtin_amdgcn_sched_barrier(0);
; #pragma unroll
;     for (int s = 0; s < 2; ++s)
; #pragma unroll
;       for (int db = 0; db < 4; ++db) O[db] = MFMA(vf[s][db], pf[s], O[db]);
;     bf16x8 vg[2][4];
; #pragma unroll
;     for (int s = 0; s < 2; ++s)
; #pragma unroll
;       for (int db = 0; db < 4; ++db) vg[s][db] = *(const bf16x8*)(Vs + (db * 32 + r) * 72 + 32 + s * 16 + h * 8);
;     bf16x8 pg[2];
;     {
;       float pv[16];
; #pragma unroll
;       for (int i = 0; i < 16; ++i) pv[i] = __builtin_amdgcn_exp2f(S1[i]);
; #pragma unroll
;       for (int i = 0; i < 8; ++i) l2 += f32x2{pv[2 * i], pv[2 * i + 1]};
; #pragma unroll
;       for (int s = 0; s < 2; ++s) {
;         u32 a0 = pack2(pv[8 * s], pv[8 * s + 1]), a1 = pack2(pv[8 * s + 2], pv[8 * s + 3]);
;         u32 a2 = pack2(pv[8 * s + 4], pv[8 * s + 5]), a3 = pack2(pv[8 * s + 6], pv[8 * s + 7]);
;         u32x4 pk = {a0, a1, a2, a3};
;         pg[s] = __builtin_bit_cast(bf16x8, pk);
;       }
;     }
.LBB0_1153:
	s_and_b32 s6, s87, 1
	s_mul_i32 s44, s6, 0x6c00
	v_add_u32_e32 v131, s44, v156
	v_lshl_add_u32 v144, v153, 1, v131
	ds_read_b128 v[160:163], v144
	ds_read_b128 v[164:167], v144 offset:32
	ds_read_b128 v[176:179], v144 offset:64
	ds_read_b128 v[180:183], v144 offset:96
	ds_read_b128 v[168:171], v144 offset:4608
	ds_read_b128 v[172:175], v144 offset:4640
	ds_read_b128 v[184:187], v144 offset:4672
	ds_read_b128 v[194:197], v144 offset:4704
	s_waitcnt lgkmcnt(7)
	v_mfma_f32_32x32x16_bf16 v[82:97], v[160:163], v[98:101], v[82:97]
	s_waitcnt lgkmcnt(6)
	v_mfma_f32_32x32x16_bf16 v[82:97], v[164:167], v[102:105], v[82:97]
	s_waitcnt lgkmcnt(5)
	v_mfma_f32_32x32x16_bf16 v[82:97], v[176:179], v[106:109], v[82:97]
	s_waitcnt lgkmcnt(4)
	v_mfma_f32_32x32x16_bf16 v[82:97], v[180:183], v[110:113], v[82:97]
	s_waitcnt lgkmcnt(3)
	v_mfma_f32_32x32x16_bf16 v[66:81], v[168:171], v[98:101], v[66:81]
	s_waitcnt lgkmcnt(2)
	v_mfma_f32_32x32x16_bf16 v[66:81], v[172:175], v[102:105], v[66:81]
	v_add3_u32 v144, s44, v0, v156
	ds_read_b128 v[160:163], v144 offset:9216
	ds_read_b128 v[164:167], v144 offset:9248
	ds_read_b128 v[168:171], v144 offset:13824
	ds_read_b128 v[172:175], v144 offset:13856
	ds_read_b128 v[176:179], v144 offset:18432
	ds_read_b128 v[180:183], v144 offset:18464
	s_waitcnt lgkmcnt(7)
	v_mfma_f32_32x32x16_bf16 v[66:81], v[184:187], v[106:109], v[66:81]
	v_exp_f32_e32 v82, v82
	v_exp_f32_e32 v83, v83
	v_exp_f32_e32 v84, v84
	v_exp_f32_e32 v85, v85
	s_waitcnt lgkmcnt(6)
	v_mfma_f32_32x32x16_bf16 v[66:81], v[194:197], v[110:113], v[66:81]
	ds_read_b128 v[184:187], v144 offset:23040
	ds_read_b128 v[194:197], v144 offset:23072
	v_exp_f32_e32 v86, v86
	v_exp_f32_e32 v87, v87
	v_exp_f32_e32 v88, v88
	v_exp_f32_e32 v89, v89
	v_exp_f32_e32 v90, v90
	v_exp_f32_e32 v91, v91
	v_exp_f32_e32 v92, v92
	v_exp_f32_e32 v93, v93
	v_exp_f32_e32 v94, v94
	v_exp_f32_e32 v95, v95
	v_exp_f32_e32 v96, v96
	v_exp_f32_e32 v97, v97
	v_add_f32_e32 v142, v142, v82
	v_add_f32_e32 v143, v143, v83
	v_add_f32_e32 v142, v84, v142
	v_add_f32_e32 v143, v85, v143
	v_add_f32_e32 v142, v86, v142
	v_add_f32_e32 v143, v87, v143
	v_add_f32_e32 v142, v88, v142
	v_add_f32_e32 v143, v89, v143
	v_add_f32_e32 v142, v90, v142
	v_add_f32_e32 v143, v91, v143
	v_add_f32_e32 v142, v92, v142
	v_add_f32_e32 v143, v93, v143
	v_add_f32_e32 v142, v94, v142
	v_add_f32_e32 v143, v95, v143
	v_add_f32_e32 v142, v96, v142
	v_add_f32_e32 v143, v97, v143
	v_cvt_pk_bf16_f32 v82, v82, v83
	v_cvt_pk_bf16_f32 v83, v84, v85
	v_cvt_pk_bf16_f32 v84, v86, v87
	v_cvt_pk_bf16_f32 v85, v88, v89
	v_cvt_pk_bf16_f32 v86, v90, v91
	v_cvt_pk_bf16_f32 v87, v92, v93
	v_cvt_pk_bf16_f32 v88, v94, v95
	v_cvt_pk_bf16_f32 v89, v96, v97
	s_waitcnt lgkmcnt(7)
	v_mfma_f32_32x32x16_bf16 v[50:65], v[160:163], v[82:85], v[50:65]
	v_exp_f32_e32 v66, v66
	v_exp_f32_e32 v67, v67
	v_exp_f32_e32 v68, v68
	v_exp_f32_e32 v69, v69
	s_waitcnt lgkmcnt(5)
	v_mfma_f32_32x32x16_bf16 v[34:49], v[168:171], v[82:85], v[34:49]
	v_exp_f32_e32 v70, v70
	v_exp_f32_e32 v71, v71
	v_exp_f32_e32 v72, v72
	v_exp_f32_e32 v73, v73
	s_waitcnt lgkmcnt(3)
	v_mfma_f32_32x32x16_bf16 v[18:33], v[176:179], v[82:85], v[18:33]
	v_exp_f32_e32 v74, v74
	v_exp_f32_e32 v75, v75
	v_exp_f32_e32 v76, v76
	v_exp_f32_e32 v77, v77
	v_mfma_f32_32x32x16_bf16 v[50:65], v[164:167], v[86:89], v[50:65]
	ds_read_b128 v[160:163], v144 offset:9312
	ds_read_b128 v[168:171], v144 offset:18528
	v_exp_f32_e32 v78, v78
	v_exp_f32_e32 v79, v79
	v_exp_f32_e32 v80, v80
	v_exp_f32_e32 v81, v81
	v_mfma_f32_32x32x16_bf16 v[34:49], v[172:175], v[86:89], v[34:49]
	ds_read_b128 v[164:167], v144 offset:13920
	ds_read_b128 v[90:93], v144 offset:18496
	ds_read_b128 v[94:97], v144 offset:23104
	v_add_f32_e32 v142, v66, v142
	v_add_f32_e32 v143, v67, v143
	v_add_f32_e32 v142, v68, v142
	v_add_f32_e32 v143, v69, v143
	s_waitcnt lgkmcnt(7)
	v_mfma_f32_32x32x16_bf16 v[18:33], v[180:183], v[86:89], v[18:33]
	ds_read_b128 v[198:201], v144 offset:9280
	v_add_f32_e32 v142, v70, v142
	v_add_f32_e32 v143, v71, v143
	v_add_f32_e32 v142, v72, v142
	v_add_f32_e32 v143, v73, v143
	s_waitcnt lgkmcnt(7)
	v_mfma_f32_32x32x16_bf16 v[2:17], v[184:187], v[82:85], v[2:17]
	v_add_f32_e32 v142, v74, v142
	v_add_f32_e32 v143, v75, v143
	v_add_f32_e32 v142, v76, v142
	v_add_f32_e32 v143, v77, v143
	s_waitcnt lgkmcnt(6)
	v_mfma_f32_32x32x16_bf16 v[2:17], v[194:197], v[86:89], v[2:17]
	ds_read_b128 v[86:89], v144 offset:13888
	ds_read_b128 v[82:85], v144 offset:23136
	v_add_f32_e32 v142, v78, v142
	v_add_f32_e32 v143, v79, v143
	v_add_f32_e32 v142, v80, v142
	v_add_f32_e32 v143, v81, v143
	v_cvt_pk_bf16_f32 v66, v66, v67
	v_cvt_pk_bf16_f32 v67, v68, v69
	v_cvt_pk_bf16_f32 v68, v70, v71
	v_cvt_pk_bf16_f32 v69, v72, v73
	v_cvt_pk_bf16_f32 v70, v74, v75
	v_cvt_pk_bf16_f32 v71, v76, v77
	v_cvt_pk_bf16_f32 v72, v78, v79
	v_cvt_pk_bf16_f32 v73, v80, v81
	s_waitcnt lgkmcnt(2)
	v_mfma_f32_32x32x16_bf16 v[50:65], v[198:201], v[66:69], v[50:65]
	s_waitcnt lgkmcnt(1)
	v_mfma_f32_32x32x16_bf16 v[34:49], v[86:89], v[66:69], v[34:49]
	s_waitcnt lgkmcnt(0)
	s_add_i32 s45, s73, s87
	s_add_i32 s7, s45, 1
	s_cmp_ge_i32 s7, s77
	s_cbranch_scc1 .Lmy_dif_w2
	s_and_b32 s6, s87, 1
	s_xor_b32 s46, s6, 1
	s_mulk_i32 s46, 0x6c00
	s_and_saveexec_b64 s[6:7], s[42:43]
	s_cbranch_execz .Lmy_dif_w1
	v_add3_u32 v144, s46, v157, v158
	s_waitcnt vmcnt(2)
	ds_write_b128 v144, v[114:117]
